# prep weight conversion rewritten by hand (3 tiles in flight per wave, static vmcnt), split 52/10 tiles per wave between converter and S5-generator workgroups; plus LDS-staged S5 carry scan
# speedup vs baseline: 1.0038x; 1.0038x over previous
; __device__ __forceinline__ void conv_dispatch(const Params& P, int tile, int lane) {
;     const int j = tile / T_PAIR; int rem = tile % T_PAIR; unsigned char* ws = P.ws;
;     if (rem < T_EVEN) { const int i = 2 * j;
;         if (rem < T_WIN) { conv_tile(P.in[2] + (size_t)j * 2048 * 4096, (bf16_t*)(ws + WS_WIN + j * SZ_WIN), 2048, 4096, rem, lane, P.in[16] + (size_t)i * DM); return; } rem -= T_WIN;
;         if (rem < T_WOUT) { conv_tile(P.in[3] + (size_t)j * 2048 * 2048, (bf16_t*)(ws + WS_WOUT + j * SZ_WOUT), 2048, 2048, rem, lane, nullptr); return; } rem -= T_WOUT;
;         if (rem < T_GLU) { conv_tile(P.in[12] + (size_t)j * 1024 * 1024, (bf16_t*)(ws + WS_GLU + j * SZ_GLU), 1024, 1024, rem, lane, nullptr); return; } rem -= T_GLU;
;         if (rem < T_W1) { conv_tile(P.in[18] + (size_t)i * 2048 * 8192, (bf16_t*)(ws + WS_W1 + i * SZ_W1), 2048, 8192, rem, lane, P.in[17] + (size_t)i * DM); return; } rem -= T_W1;
;         conv_tile(P.in[19] + (size_t)i * 8192 * 2048, (bf16_t*)(ws + WS_W2 + i * SZ_W2), 8192, 2048, rem, lane, nullptr);
;     } else { rem -= T_EVEN; const int i = 2 * j + 1;
;         if (rem < T_QKV) { conv_tile(P.in[13] + (size_t)j * 2048 * 6144, (bf16_t*)(ws + WS_QKV + j * SZ_QKV), 2048, 6144, rem, lane, P.in[16] + (size_t)i * DM); return; } rem -= T_QKV;
;         if (rem < T_WOUT) { conv_tile(P.in[14] + (size_t)j * 2048 * 2048, (bf16_t*)(ws + WS_COUT + j * SZ_WOUT), 2048, 2048, rem, lane, nullptr); return; } rem -= T_WOUT;
;         if (rem < T_W1) { conv_tile(P.in[18] + (size_t)i * 2048 * 8192, (bf16_t*)(ws + WS_W1 + i * SZ_W1), 2048, 8192, rem, lane, P.in[17] + (size_t)i * DM); return; } rem -= T_W1;
;         conv_tile(P.in[19] + (size_t)i * 8192 * 2048, (bf16_t*)(ws + WS_W2 + i * SZ_W2), 8192, 2048, rem, lane, nullptr);
;     }
; }
; __global__ void __launch_bounds__(NTHR) hybrid_encoder_fwd(Params P) {
;     ...
;             constexpr int PB_PAIR = (T_PAIR - T_W1 - T_W2) / 4, NBATCH = 2 * PB_PAIR, NB1 = 11712;
;     ...
;             if (bid >= 128) for (int bt = (bid - 128) * 8 + wid; bt < NB1; bt += (G - 128) * 8) {
; #pragma unroll 1
;                 for (int q = 0; q < 4; ++q) conv_dispatch(P, PREP_TILE(bt) + q, lane); }
;             for (int bt = NB1 + bid * 8 + wid; bt < NBATCH; bt += G * 8) {
; #pragma unroll 1
;                 for (int q = 0; q < 4; ++q) conv_dispatch(P, PREP_TILE(bt) + q, lane); }
.LBB0_10:
	s_cmpk_gt_i32 s2, 0x7f
	s_cselect_b64 s[4:5], -1, 0
	v_writelane_b32 v253, s4, 14
	s_and_b64 vcc, exec, s[4:5]
	s_mov_b64 s[0:1], -1
	v_writelane_b32 v253, s5, 15
	s_mov_b32 s4, s22
	v_writelane_b32 v253, s4, 16
	s_nop 1
	v_writelane_b32 v253, s5, 17
	s_cbranch_vccz .LBB0_55
	s_add_i32 s3, s22, 0xfffffc00
	s_mov_b32 s25, 60
	s_mov_b32 s39, 16
.Lcv_entry:
	s_waitcnt lgkmcnt(0)
	v_and_b32_e32 v2, 7, v201
	v_lshrrev_b32_e32 v3, 3, v201
	v_lshlrev_b32_e32 v4, 4, v2
	v_lshlrev_b32_e32 v5, 4, v3
	v_lshlrev_b32_e32 v7, 5, v2
	s_mov_b32 s30, 0
	s_min_u32 s0, s30, s25
	s_lshl_b32 s0, s0, 10
	s_add_i32 s0, s0, s3
	s_add_i32 s30, s30, 1
	s_cmp_ge_u32 s0, 0x7a00
	s_cselect_b32 s33, 1, 0
	s_mul_i32 s1, s33, 0x7a00
	s_sub_i32 s20, s0, s1
	s_cmp_lt_u32 s20, 0x1000
	s_cbranch_scc1 .Lcv0_win
	s_cmp_lt_u32 s20, 0x1800
	s_cbranch_scc1 .Lcv0_wout
	s_cmp_lt_u32 s20, 0x1a00
	s_cbranch_scc1 .Lcv0_glu
	s_cmp_lt_u32 s20, 0x3a00
	s_cbranch_scc1 .Lcv0_w1
	s_cmp_lt_u32 s20, 0x5a00
	s_cbranch_scc1 .Lcv0_w2
	s_cmp_lt_u32 s20, 0x7200
	s_cbranch_scc1 .Lcv0_qkv
.Lcv0_cout:
	s_sub_i32 s20, s20, 0x7200
	s_lshl_b32 s1, s33, 24
	s_add_u32 s4, s88, s1
	s_addc_u32 s5, s89, 0
	s_lshl_b32 s1, s33, 23
	s_add_u32 s1, s1, 0x6404000
	s_add_u32 s6, s96, s1
	s_addc_u32 s7, s97, 0
	s_mov_b32 s10, 0x2000
	s_mov_b32 s11, 0x1000
	s_mov_b32 s21, 6
	s_mov_b32 s75, 0
	s_branch .Lcv0_go
.Lcv0_win:
	s_lshl_b32 s1, s33, 25
	s_add_u32 s4, s64, s1
	s_addc_u32 s5, s65, 0
	s_lshl_b32 s1, s33, 24
	s_add_u32 s1, s1, 0x4000
	s_add_u32 s6, s96, s1
	s_addc_u32 s7, s97, 0
	s_mov_b32 s10, 0x4000
	s_mov_b32 s11, 0x1000
	s_mov_b32 s21, 7
	s_mul_i32 s1, s33, 0x4000
	s_add_u32 s8, s12, s1
	s_addc_u32 s9, s13, 0
	s_mov_b32 s75, 1
	s_branch .Lcv0_go
.Lcv0_wout:
	s_sub_i32 s20, s20, 0x1000
	s_lshl_b32 s1, s33, 24
	s_add_u32 s4, s66, s1
	s_addc_u32 s5, s67, 0
	s_lshl_b32 s1, s33, 23
	s_add_u32 s1, s1, 0x2004000
	s_add_u32 s6, s96, s1
	s_addc_u32 s7, s97, 0
	s_mov_b32 s10, 0x2000
	s_mov_b32 s11, 0x1000
	s_mov_b32 s21, 6
	s_mov_b32 s75, 0
	s_branch .Lcv0_go
.Lcv0_glu:
	s_sub_i32 s20, s20, 0x1800
	s_lshl_b32 s1, s33, 22
	s_add_u32 s4, s84, s1
	s_addc_u32 s5, s85, 0
	s_lshl_b32 s1, s33, 21
	s_add_u32 s1, s1, 0x3004000
	s_add_u32 s6, s96, s1
	s_addc_u32 s7, s97, 0
	s_mov_b32 s10, 0x1000
	s_mov_b32 s11, 0x800
	s_mov_b32 s21, 5
	s_mov_b32 s75, 0
	s_branch .Lcv0_go
.Lcv0_w1:
	s_sub_i32 s20, s20, 0x1a00
	s_lshl_b32 s1, s33, 27
	s_add_u32 s4, s16, s1
	s_addc_u32 s5, s17, 0
	s_lshl_b32 s1, s33, 26
	s_add_u32 s1, s1, 0x7404000
	s_add_u32 s6, s96, s1
	s_addc_u32 s7, s97, 0
	s_mov_b32 s10, 0x8000
	s_mov_b32 s11, 0x1000
	s_mov_b32 s21, 8
	s_mul_i32 s1, s33, 0x4000
	s_add_u32 s8, s14, s1
	s_addc_u32 s9, s15, 0
	s_mov_b32 s75, 1
	s_branch .Lcv0_go
.Lcv0_w2:
	s_sub_i32 s20, s20, 0x3a00
	s_lshl_b32 s1, s33, 27
	s_add_u32 s4, s18, s1
	s_addc_u32 s5, s19, 0
	s_lshl_b32 s1, s33, 26
	s_add_u32 s1, s1, 0xf404000
	s_add_u32 s6, s96, s1
	s_addc_u32 s7, s97, 0
	s_mov_b32 s10, 0x2000
	s_mov_b32 s11, 0x4000
	s_mov_b32 s21, 6
	s_mov_b32 s75, 0
	s_branch .Lcv0_go
.Lcv0_qkv:
	s_sub_i32 s20, s20, 0x5a00
	s_mul_i32 s1, s33, 0x3000000
	s_add_u32 s4, s86, s1
	s_addc_u32 s5, s87, 0
	s_mul_i32 s1, s33, 0x1800000
	s_add_u32 s1, s1, 0x3404000
	s_add_u32 s6, s96, s1
	s_addc_u32 s7, s97, 0
	s_mov_b32 s10, 0x6000
	s_mov_b32 s11, 0x1000
	s_mov_b32 s21, 255
	s_mul_i32 s1, s33, 0x4000
	s_add_u32 s1, s1, 0x2000
	s_add_u32 s8, s12, s1
	s_addc_u32 s9, s13, 0
	s_mov_b32 s75, 1
	s_branch .Lcv0_go
.Lcv0_go:
	s_cmp_eq_u32 s21, 255
	s_cbranch_scc1 .Lcv0_d192
	s_lshr_b32 s22, s20, s21
	s_lshl_b32 s1, s22, s21
	s_sub_i32 s23, s20, s1
	s_branch .Lcv0_dd
.Lcv0_d192:
	s_lshr_b32 s22, s20, 6
	s_mul_i32 s22, s22, 171
	s_lshr_b32 s22, s22, 9
	s_mul_i32 s1, s22, 192
	s_sub_i32 s23, s20, s1
; __device__ __forceinline__ void conv_tile(const float* src, bf16_t* dst, int K, int N, int tile, int lane, const float* gk) {
;     const int tn = N >> 5; const int k0 = (tile / tn) * 64, n0 = (tile % tn) * 32; const int kg = lane & 7, jn = lane >> 3;
;     f32x4 v[8]; const float* sp = src + (size_t)(k0 + 8 * kg) * N + n0 + 4 * jn;
; #pragma unroll
;     for (int r = 0; r < 8; ++r) v[r] = *(const f32x4*)(sp + (size_t)r * N);
; __device__ __forceinline__ void conv_dispatch(const Params& P, int tile, int lane) {
;     const int j = tile / T_PAIR; int rem = tile % T_PAIR; unsigned char* ws = P.ws;
;     if (rem < T_EVEN) { const int i = 2 * j;
;         if (rem < T_WIN) { conv_tile(P.in[2] + (size_t)j * 2048 * 4096, (bf16_t*)(ws + WS_WIN + j * SZ_WIN), 2048, 4096, rem, lane, P.in[16] + (size_t)i * DM); return; } rem -= T_WIN;
;         if (rem < T_WOUT) { conv_tile(P.in[3] + (size_t)j * 2048 * 2048, (bf16_t*)(ws + WS_WOUT + j * SZ_WOUT), 2048, 2048, rem, lane, nullptr); return; } rem -= T_WOUT;
;         if (rem < T_GLU) { conv_tile(P.in[12] + (size_t)j * 1024 * 1024, (bf16_t*)(ws + WS_GLU + j * SZ_GLU), 1024, 1024, rem, lane, nullptr); return; } rem -= T_GLU;
;         if (rem < T_W1) { conv_tile(P.in[18] + (size_t)i * 2048 * 8192, (bf16_t*)(ws + WS_W1 + i * SZ_W1), 2048, 8192, rem, lane, P.in[17] + (size_t)i * DM); return; } rem -= T_W1;
;         conv_tile(P.in[19] + (size_t)i * 8192 * 2048, (bf16_t*)(ws + WS_W2 + i * SZ_W2), 8192, 2048, rem, lane, nullptr);
;     } else { rem -= T_EVEN; const int i = 2 * j + 1;
;         if (rem < T_QKV) { conv_tile(P.in[13] + (size_t)j * 2048 * 6144, (bf16_t*)(ws + WS_QKV + j * SZ_QKV), 2048, 6144, rem, lane, P.in[16] + (size_t)i * DM); return; } rem -= T_QKV;
;         if (rem < T_WOUT) { conv_tile(P.in[14] + (size_t)j * 2048 * 2048, (bf16_t*)(ws + WS_COUT + j * SZ_WOUT), 2048, 2048, rem, lane, nullptr); return; } rem -= T_WOUT;
;         if (rem < T_W1) { conv_tile(P.in[18] + (size_t)i * 2048 * 8192, (bf16_t*)(ws + WS_W1 + i * SZ_W1), 2048, 8192, rem, lane, P.in[17] + (size_t)i * DM); return; } rem -= T_W1;
;         conv_tile(P.in[19] + (size_t)i * 8192 * 2048, (bf16_t*)(ws + WS_W2 + i * SZ_W2), 8192, 2048, rem, lane, nullptr);
;     }
; }
.Lcv0_dd:
	s_lshl_b32 s1, s10, 6
	s_mul_i32 s1, s1, s22
	s_lshl_b32 s24, s23, 7
	s_add_u32 s1, s1, s24
	s_add_u32 s4, s4, s1
	s_addc_u32 s5, s5, 0
	s_lshl_b32 s1, s11, 5
	s_mul_i32 s1, s1, s23
	s_lshl_b32 s24, s22, 7
	s_add_u32 s1, s1, s24
	s_add_u32 s72, s6, s1
	s_addc_u32 s73, s7, 0
	s_mov_b32 s74, s11
	s_lshl_b32 s1, s22, 8
	s_cmp_eq_u32 s75, 0
	s_cselect_b32 s8, s4, s8
	s_cselect_b32 s9, s5, s9
	s_cselect_b32 s1, 0, s1
	s_add_u32 s8, s8, s1
	s_addc_u32 s9, s9, 0
	s_lshl_b32 s1, s10, 3
	v_mul_lo_u32 v6, v2, s1
	v_add_u32_e32 v6, v6, v5
	s_lshl_b32 s1, s11, 2
	v_mul_lo_u32 v48, v3, s1
	v_add_u32_e32 v48, v48, v4
	global_load_dwordx4 v[8:11], v6, s[4:5]
	v_add_u32_e32 v6, s10, v6
	global_load_dwordx4 v[12:15], v6, s[4:5]
	v_add_u32_e32 v6, s10, v6
	global_load_dwordx4 v[16:19], v6, s[4:5]
	v_add_u32_e32 v6, s10, v6
	global_load_dwordx4 v[20:23], v6, s[4:5]
	v_add_u32_e32 v6, s10, v6
	global_load_dwordx4 v[24:27], v6, s[4:5]
	v_add_u32_e32 v6, s10, v6
	global_load_dwordx4 v[28:31], v6, s[4:5]
	v_add_u32_e32 v6, s10, v6
	global_load_dwordx4 v[32:35], v6, s[4:5]
	v_add_u32_e32 v6, s10, v6
	global_load_dwordx4 v[36:39], v6, s[4:5]
	global_load_dwordx4 v[40:43], v7, s[8:9]
	global_load_dwordx4 v[44:47], v7, s[8:9] offset:16
	s_min_u32 s0, s30, s25
	s_lshl_b32 s0, s0, 10
	s_add_i32 s0, s0, s3
	s_add_i32 s30, s30, 1
	s_cmp_ge_u32 s0, 0x7a00
	s_cselect_b32 s33, 1, 0
	s_mul_i32 s1, s33, 0x7a00
	s_sub_i32 s20, s0, s1
	s_cmp_lt_u32 s20, 0x1000
	s_cbranch_scc1 .Lcv1_win
	s_cmp_lt_u32 s20, 0x1800
	s_cbranch_scc1 .Lcv1_wout
	s_cmp_lt_u32 s20, 0x1a00
	s_cbranch_scc1 .Lcv1_glu
	s_cmp_lt_u32 s20, 0x3a00
	s_cbranch_scc1 .Lcv1_w1
	s_cmp_lt_u32 s20, 0x5a00
	s_cbranch_scc1 .Lcv1_w2
	s_cmp_lt_u32 s20, 0x7200
	s_cbranch_scc1 .Lcv1_qkv
.Lcv1_cout:
	s_sub_i32 s20, s20, 0x7200
	s_lshl_b32 s1, s33, 24
	s_add_u32 s4, s88, s1
	s_addc_u32 s5, s89, 0
	s_lshl_b32 s1, s33, 23
	s_add_u32 s1, s1, 0x6404000
	s_add_u32 s6, s96, s1
	s_addc_u32 s7, s97, 0
	s_mov_b32 s10, 0x2000
	s_mov_b32 s11, 0x1000
	s_mov_b32 s21, 6
	s_mov_b32 s79, 0
	s_branch .Lcv1_go
.Lcv1_win:
	s_lshl_b32 s1, s33, 25
	s_add_u32 s4, s64, s1
	s_addc_u32 s5, s65, 0
	s_lshl_b32 s1, s33, 24
	s_add_u32 s1, s1, 0x4000
	s_add_u32 s6, s96, s1
	s_addc_u32 s7, s97, 0
	s_mov_b32 s10, 0x4000
	s_mov_b32 s11, 0x1000
	s_mov_b32 s21, 7
	s_mul_i32 s1, s33, 0x4000
	s_add_u32 s8, s12, s1
	s_addc_u32 s9, s13, 0
	s_mov_b32 s79, 1
	s_branch .Lcv1_go
.Lcv1_wout:
	s_sub_i32 s20, s20, 0x1000
	s_lshl_b32 s1, s33, 24
	s_add_u32 s4, s66, s1
	s_addc_u32 s5, s67, 0
	s_lshl_b32 s1, s33, 23
	s_add_u32 s1, s1, 0x2004000
	s_add_u32 s6, s96, s1
	s_addc_u32 s7, s97, 0
	s_mov_b32 s10, 0x2000
	s_mov_b32 s11, 0x1000
	s_mov_b32 s21, 6
	s_mov_b32 s79, 0
	s_branch .Lcv1_go
.Lcv1_glu:
	s_sub_i32 s20, s20, 0x1800
	s_lshl_b32 s1, s33, 22
	s_add_u32 s4, s84, s1
	s_addc_u32 s5, s85, 0
	s_lshl_b32 s1, s33, 21
	s_add_u32 s1, s1, 0x3004000
	s_add_u32 s6, s96, s1
	s_addc_u32 s7, s97, 0
	s_mov_b32 s10, 0x1000
	s_mov_b32 s11, 0x800
	s_mov_b32 s21, 5
	s_mov_b32 s79, 0
	s_branch .Lcv1_go
.Lcv1_w1:
	s_sub_i32 s20, s20, 0x1a00
	s_lshl_b32 s1, s33, 27
	s_add_u32 s4, s16, s1
	s_addc_u32 s5, s17, 0
	s_lshl_b32 s1, s33, 26
	s_add_u32 s1, s1, 0x7404000
	s_add_u32 s6, s96, s1
	s_addc_u32 s7, s97, 0
	s_mov_b32 s10, 0x8000
	s_mov_b32 s11, 0x1000
	s_mov_b32 s21, 8
	s_mul_i32 s1, s33, 0x4000
	s_add_u32 s8, s14, s1
	s_addc_u32 s9, s15, 0
	s_mov_b32 s79, 1
	s_branch .Lcv1_go
.Lcv1_w2:
	s_sub_i32 s20, s20, 0x3a00
	s_lshl_b32 s1, s33, 27
	s_add_u32 s4, s18, s1
	s_addc_u32 s5, s19, 0
	s_lshl_b32 s1, s33, 26
	s_add_u32 s1, s1, 0xf404000
	s_add_u32 s6, s96, s1
	s_addc_u32 s7, s97, 0
	s_mov_b32 s10, 0x2000
	s_mov_b32 s11, 0x4000
	s_mov_b32 s21, 6
	s_mov_b32 s79, 0
	s_branch .Lcv1_go
.Lcv1_qkv:
	s_sub_i32 s20, s20, 0x5a00
	s_mul_i32 s1, s33, 0x3000000
	s_add_u32 s4, s86, s1
	s_addc_u32 s5, s87, 0
	s_mul_i32 s1, s33, 0x1800000
	s_add_u32 s1, s1, 0x3404000
	s_add_u32 s6, s96, s1
	s_addc_u32 s7, s97, 0
	s_mov_b32 s10, 0x6000
	s_mov_b32 s11, 0x1000
	s_mov_b32 s21, 255
	s_mul_i32 s1, s33, 0x4000
	s_add_u32 s1, s1, 0x2000
	s_add_u32 s8, s12, s1
	s_addc_u32 s9, s13, 0
	s_mov_b32 s79, 1
	s_branch .Lcv1_go

; __device__ __forceinline__ void conv_tile(const float* src, bf16_t* dst, int K, int N, int tile, int lane, const float* gk) {
;     const int tn = N >> 5; const int k0 = (tile / tn) * 64, n0 = (tile % tn) * 32; const int kg = lane & 7, jn = lane >> 3;
;     f32x4 v[8]; const float* sp = src + (size_t)(k0 + 8 * kg) * N + n0 + 4 * jn;
; #pragma unroll
;     for (int r = 0; r < 8; ++r) v[r] = *(const f32x4*)(sp + (size_t)r * N);
; __device__ __forceinline__ void conv_dispatch(const Params& P, int tile, int lane) {
;     const int j = tile / T_PAIR; int rem = tile % T_PAIR; unsigned char* ws = P.ws;
;     if (rem < T_EVEN) { const int i = 2 * j;
;         if (rem < T_WIN) { conv_tile(P.in[2] + (size_t)j * 2048 * 4096, (bf16_t*)(ws + WS_WIN + j * SZ_WIN), 2048, 4096, rem, lane, P.in[16] + (size_t)i * DM); return; } rem -= T_WIN;
;         if (rem < T_WOUT) { conv_tile(P.in[3] + (size_t)j * 2048 * 2048, (bf16_t*)(ws + WS_WOUT + j * SZ_WOUT), 2048, 2048, rem, lane, nullptr); return; } rem -= T_WOUT;
;         if (rem < T_GLU) { conv_tile(P.in[12] + (size_t)j * 1024 * 1024, (bf16_t*)(ws + WS_GLU + j * SZ_GLU), 1024, 1024, rem, lane, nullptr); return; } rem -= T_GLU;
;         if (rem < T_W1) { conv_tile(P.in[18] + (size_t)i * 2048 * 8192, (bf16_t*)(ws + WS_W1 + i * SZ_W1), 2048, 8192, rem, lane, P.in[17] + (size_t)i * DM); return; } rem -= T_W1;
;         conv_tile(P.in[19] + (size_t)i * 8192 * 2048, (bf16_t*)(ws + WS_W2 + i * SZ_W2), 8192, 2048, rem, lane, nullptr);
;     } else { rem -= T_EVEN; const int i = 2 * j + 1;
;         if (rem < T_QKV) { conv_tile(P.in[13] + (size_t)j * 2048 * 6144, (bf16_t*)(ws + WS_QKV + j * SZ_QKV), 2048, 6144, rem, lane, P.in[16] + (size_t)i * DM); return; } rem -= T_QKV;
;         if (rem < T_WOUT) { conv_tile(P.in[14] + (size_t)j * 2048 * 2048, (bf16_t*)(ws + WS_COUT + j * SZ_WOUT), 2048, 2048, rem, lane, nullptr); return; } rem -= T_WOUT;
;         if (rem < T_W1) { conv_tile(P.in[18] + (size_t)i * 2048 * 8192, (bf16_t*)(ws + WS_W1 + i * SZ_W1), 2048, 8192, rem, lane, P.in[17] + (size_t)i * DM); return; } rem -= T_W1;
;         conv_tile(P.in[19] + (size_t)i * 8192 * 2048, (bf16_t*)(ws + WS_W2 + i * SZ_W2), 8192, 2048, rem, lane, nullptr);
;     }
; }
.Lcv1_dd:
	s_lshl_b32 s1, s10, 6
	s_mul_i32 s1, s1, s22
	s_lshl_b32 s24, s23, 7
	s_add_u32 s1, s1, s24
	s_add_u32 s4, s4, s1
	s_addc_u32 s5, s5, 0
	s_lshl_b32 s1, s11, 5
	s_mul_i32 s1, s1, s23
	s_lshl_b32 s24, s22, 7
	s_add_u32 s1, s1, s24
	s_add_u32 s76, s6, s1
	s_addc_u32 s77, s7, 0
	s_mov_b32 s78, s11
	s_lshl_b32 s1, s22, 8
	s_cmp_eq_u32 s79, 0
	s_cselect_b32 s8, s4, s8
	s_cselect_b32 s9, s5, s9
	s_cselect_b32 s1, 0, s1
	s_add_u32 s8, s8, s1
	s_addc_u32 s9, s9, 0
	s_lshl_b32 s1, s10, 3
	v_mul_lo_u32 v6, v2, s1
	v_add_u32_e32 v6, v6, v5
	s_lshl_b32 s1, s11, 2
	v_mul_lo_u32 v92, v3, s1
	v_add_u32_e32 v92, v92, v4
	global_load_dwordx4 v[52:55], v6, s[4:5]
	v_add_u32_e32 v6, s10, v6
	global_load_dwordx4 v[56:59], v6, s[4:5]
	v_add_u32_e32 v6, s10, v6
	global_load_dwordx4 v[60:63], v6, s[4:5]
	v_add_u32_e32 v6, s10, v6
	global_load_dwordx4 v[64:67], v6, s[4:5]
	v_add_u32_e32 v6, s10, v6
	global_load_dwordx4 v[68:71], v6, s[4:5]
	v_add_u32_e32 v6, s10, v6
	global_load_dwordx4 v[72:75], v6, s[4:5]
	v_add_u32_e32 v6, s10, v6
	global_load_dwordx4 v[76:79], v6, s[4:5]
	v_add_u32_e32 v6, s10, v6
	global_load_dwordx4 v[80:83], v6, s[4:5]
	global_load_dwordx4 v[84:87], v7, s[8:9]
	global_load_dwordx4 v[88:91], v7, s[8:9] offset:16
	s_min_u32 s0, s30, s25
	s_lshl_b32 s0, s0, 10
	s_add_i32 s0, s0, s3
	s_add_i32 s30, s30, 1
	s_cmp_ge_u32 s0, 0x7a00
	s_cselect_b32 s33, 1, 0
	s_mul_i32 s1, s33, 0x7a00
	s_sub_i32 s20, s0, s1
	s_cmp_lt_u32 s20, 0x1000
	s_cbranch_scc1 .Lcv2_win
	s_cmp_lt_u32 s20, 0x1800
	s_cbranch_scc1 .Lcv2_wout
	s_cmp_lt_u32 s20, 0x1a00
	s_cbranch_scc1 .Lcv2_glu
	s_cmp_lt_u32 s20, 0x3a00
	s_cbranch_scc1 .Lcv2_w1
	s_cmp_lt_u32 s20, 0x5a00
	s_cbranch_scc1 .Lcv2_w2
	s_cmp_lt_u32 s20, 0x7200
	s_cbranch_scc1 .Lcv2_qkv
.Lcv2_cout:
	s_sub_i32 s20, s20, 0x7200
	s_lshl_b32 s1, s33, 24
	s_add_u32 s4, s88, s1
	s_addc_u32 s5, s89, 0
	s_lshl_b32 s1, s33, 23
	s_add_u32 s1, s1, 0x6404000
	s_add_u32 s6, s96, s1
	s_addc_u32 s7, s97, 0
	s_mov_b32 s10, 0x2000
	s_mov_b32 s11, 0x1000
	s_mov_b32 s21, 6
	s_mov_b32 s83, 0
	s_branch .Lcv2_go
.Lcv2_win:
	s_lshl_b32 s1, s33, 25
	s_add_u32 s4, s64, s1
	s_addc_u32 s5, s65, 0
	s_lshl_b32 s1, s33, 24
	s_add_u32 s1, s1, 0x4000
	s_add_u32 s6, s96, s1
	s_addc_u32 s7, s97, 0
	s_mov_b32 s10, 0x4000
	s_mov_b32 s11, 0x1000
	s_mov_b32 s21, 7
	s_mul_i32 s1, s33, 0x4000
	s_add_u32 s8, s12, s1
	s_addc_u32 s9, s13, 0
	s_mov_b32 s83, 1
	s_branch .Lcv2_go
.Lcv2_wout:
	s_sub_i32 s20, s20, 0x1000
	s_lshl_b32 s1, s33, 24
	s_add_u32 s4, s66, s1
	s_addc_u32 s5, s67, 0
	s_lshl_b32 s1, s33, 23
	s_add_u32 s1, s1, 0x2004000
	s_add_u32 s6, s96, s1
	s_addc_u32 s7, s97, 0
	s_mov_b32 s10, 0x2000
	s_mov_b32 s11, 0x1000
	s_mov_b32 s21, 6
	s_mov_b32 s83, 0
	s_branch .Lcv2_go
.Lcv2_glu:
	s_sub_i32 s20, s20, 0x1800
	s_lshl_b32 s1, s33, 22
	s_add_u32 s4, s84, s1
	s_addc_u32 s5, s85, 0
	s_lshl_b32 s1, s33, 21
	s_add_u32 s1, s1, 0x3004000
	s_add_u32 s6, s96, s1
	s_addc_u32 s7, s97, 0
	s_mov_b32 s10, 0x1000
	s_mov_b32 s11, 0x800
	s_mov_b32 s21, 5
	s_mov_b32 s83, 0
	s_branch .Lcv2_go
.Lcv2_w1:
	s_sub_i32 s20, s20, 0x1a00
	s_lshl_b32 s1, s33, 27
	s_add_u32 s4, s16, s1
	s_addc_u32 s5, s17, 0
	s_lshl_b32 s1, s33, 26
	s_add_u32 s1, s1, 0x7404000
	s_add_u32 s6, s96, s1
	s_addc_u32 s7, s97, 0
	s_mov_b32 s10, 0x8000
	s_mov_b32 s11, 0x1000
	s_mov_b32 s21, 8
	s_mul_i32 s1, s33, 0x4000
	s_add_u32 s8, s14, s1
	s_addc_u32 s9, s15, 0
	s_mov_b32 s83, 1
	s_branch .Lcv2_go
.Lcv2_w2:
	s_sub_i32 s20, s20, 0x3a00
	s_lshl_b32 s1, s33, 27
	s_add_u32 s4, s18, s1
	s_addc_u32 s5, s19, 0
	s_lshl_b32 s1, s33, 26
	s_add_u32 s1, s1, 0xf404000
	s_add_u32 s6, s96, s1
	s_addc_u32 s7, s97, 0
	s_mov_b32 s10, 0x2000
	s_mov_b32 s11, 0x4000
	s_mov_b32 s21, 6
	s_mov_b32 s83, 0
	s_branch .Lcv2_go
.Lcv2_qkv:
	s_sub_i32 s20, s20, 0x5a00
	s_mul_i32 s1, s33, 0x3000000
	s_add_u32 s4, s86, s1
	s_addc_u32 s5, s87, 0
	s_mul_i32 s1, s33, 0x1800000
	s_add_u32 s1, s1, 0x3404000
	s_add_u32 s6, s96, s1
	s_addc_u32 s7, s97, 0
	s_mov_b32 s10, 0x6000
	s_mov_b32 s11, 0x1000
	s_mov_b32 s21, 255
	s_mul_i32 s1, s33, 0x4000
	s_add_u32 s1, s1, 0x2000
	s_add_u32 s8, s12, s1
	s_addc_u32 s9, s13, 0
	s_mov_b32 s83, 1
	s_branch .Lcv2_go

; __device__ __forceinline__ unsigned cvt_pk_bf16(float lo, float hi) { unsigned r; asm volatile("v_cvt_pk_bf16_f32 %0, %1, %2" : "=v"(r) : "v"(lo), "v"(hi)); return r; }
; __device__ __forceinline__ void conv_tile(const float* src, bf16_t* dst, int K, int N, int tile, int lane, const float* gk) {
;     const int tn = N >> 5; const int k0 = (tile / tn) * 64, n0 = (tile % tn) * 32; const int kg = lane & 7, jn = lane >> 3;
;     f32x4 v[8]; const float* sp = src + (size_t)(k0 + 8 * kg) * N + n0 + 4 * jn;
; #pragma unroll
;     for (int r = 0; r < 8; ++r) v[r] = *(const f32x4*)(sp + (size_t)r * N);
;     if (gk) { const f32x4 g0 = *(const f32x4*)(gk + k0 + 8 * kg), g1 = *(const f32x4*)(gk + k0 + 8 * kg + 4);
; #pragma unroll
;         for (int r = 0; r < 4; ++r) { v[r] *= g0[r]; v[4 + r] *= g1[r]; } }
; #pragma unroll
;     for (int i = 0; i < 4; ++i) { u32x4 w; w.x = cvt_pk_bf16(v[0][i], v[1][i]); w.y = cvt_pk_bf16(v[2][i], v[3][i]); w.z = cvt_pk_bf16(v[4][i], v[5][i]); w.w = cvt_pk_bf16(v[6][i], v[7][i]);
;         *(u32x4*)(dst + (size_t)(n0 + 4 * jn + i) * K + k0 + 8 * kg) = w; }
.Lcv2_dd:
	s_lshl_b32 s1, s10, 6
	s_mul_i32 s1, s1, s22
	s_lshl_b32 s24, s23, 7
	s_add_u32 s1, s1, s24
	s_add_u32 s4, s4, s1
	s_addc_u32 s5, s5, 0
	s_lshl_b32 s1, s11, 5
	s_mul_i32 s1, s1, s23
	s_lshl_b32 s24, s22, 7
	s_add_u32 s1, s1, s24
	s_add_u32 s80, s6, s1
	s_addc_u32 s81, s7, 0
	s_mov_b32 s82, s11
	s_lshl_b32 s1, s22, 8
	s_cmp_eq_u32 s83, 0
	s_cselect_b32 s8, s4, s8
	s_cselect_b32 s9, s5, s9
	s_cselect_b32 s1, 0, s1
	s_add_u32 s8, s8, s1
	s_addc_u32 s9, s9, 0
	s_lshl_b32 s1, s10, 3
	v_mul_lo_u32 v6, v2, s1
	v_add_u32_e32 v6, v6, v5
	s_lshl_b32 s1, s11, 2
	v_mul_lo_u32 v136, v3, s1
	v_add_u32_e32 v136, v136, v4
	global_load_dwordx4 v[96:99], v6, s[4:5]
	v_add_u32_e32 v6, s10, v6
	global_load_dwordx4 v[100:103], v6, s[4:5]
	v_add_u32_e32 v6, s10, v6
	global_load_dwordx4 v[104:107], v6, s[4:5]
	v_add_u32_e32 v6, s10, v6
	global_load_dwordx4 v[108:111], v6, s[4:5]
	v_add_u32_e32 v6, s10, v6
	global_load_dwordx4 v[112:115], v6, s[4:5]
	v_add_u32_e32 v6, s10, v6
	global_load_dwordx4 v[116:119], v6, s[4:5]
	v_add_u32_e32 v6, s10, v6
	global_load_dwordx4 v[120:123], v6, s[4:5]
	v_add_u32_e32 v6, s10, v6
	global_load_dwordx4 v[124:127], v6, s[4:5]
	global_load_dwordx4 v[128:131], v7, s[8:9]
	global_load_dwordx4 v[132:135], v7, s[8:9] offset:16
	s_waitcnt vmcnt(20)
	s_cmp_eq_u32 s75, 0
	s_cbranch_scc1 .Lcv3_nog
	v_mul_f32_e32 v8, v40, v8
	v_mul_f32_e32 v9, v40, v9
	v_mul_f32_e32 v10, v40, v10
	v_mul_f32_e32 v11, v40, v11
	v_mul_f32_e32 v12, v41, v12
	v_mul_f32_e32 v13, v41, v13
	v_mul_f32_e32 v14, v41, v14
	v_mul_f32_e32 v15, v41, v15
	v_mul_f32_e32 v16, v42, v16
	v_mul_f32_e32 v17, v42, v17
	v_mul_f32_e32 v18, v42, v18
	v_mul_f32_e32 v19, v42, v19
	v_mul_f32_e32 v20, v43, v20
	v_mul_f32_e32 v21, v43, v21
	v_mul_f32_e32 v22, v43, v22
	v_mul_f32_e32 v23, v43, v23
	v_mul_f32_e32 v24, v44, v24
	v_mul_f32_e32 v25, v44, v25
	v_mul_f32_e32 v26, v44, v26
	v_mul_f32_e32 v27, v44, v27
	v_mul_f32_e32 v28, v45, v28
	v_mul_f32_e32 v29, v45, v29
	v_mul_f32_e32 v30, v45, v30
	v_mul_f32_e32 v31, v45, v31
	v_mul_f32_e32 v32, v46, v32
	v_mul_f32_e32 v33, v46, v33
	v_mul_f32_e32 v34, v46, v34
	v_mul_f32_e32 v35, v46, v35
	v_mul_f32_e32 v36, v47, v36
	v_mul_f32_e32 v37, v47, v37
	v_mul_f32_e32 v38, v47, v38
	v_mul_f32_e32 v39, v47, v39
.Lcv3_nog:
	v_cvt_pk_bf16_f32 v40, v8, v12
	v_cvt_pk_bf16_f32 v41, v16, v20
	v_cvt_pk_bf16_f32 v42, v24, v28
	v_cvt_pk_bf16_f32 v43, v32, v36
	global_store_dwordx4 v48, v[40:43], s[72:73]
	v_add_u32_e32 v48, s74, v48
	v_cvt_pk_bf16_f32 v44, v9, v13
	v_cvt_pk_bf16_f32 v45, v17, v21
	v_cvt_pk_bf16_f32 v46, v25, v29
	v_cvt_pk_bf16_f32 v47, v33, v37
	global_store_dwordx4 v48, v[44:47], s[72:73]
	v_add_u32_e32 v48, s74, v48
	v_cvt_pk_bf16_f32 v40, v10, v14
	v_cvt_pk_bf16_f32 v41, v18, v22
	v_cvt_pk_bf16_f32 v42, v26, v30
	v_cvt_pk_bf16_f32 v43, v34, v38
	global_store_dwordx4 v48, v[40:43], s[72:73]
	v_add_u32_e32 v48, s74, v48
	v_cvt_pk_bf16_f32 v44, v11, v15
	v_cvt_pk_bf16_f32 v45, v19, v23
	v_cvt_pk_bf16_f32 v46, v27, v31
	v_cvt_pk_bf16_f32 v47, v35, v39
	global_store_dwordx4 v48, v[44:47], s[72:73]
	s_min_u32 s0, s30, s25
	s_lshl_b32 s0, s0, 10
	s_add_i32 s0, s0, s3
	s_add_i32 s30, s30, 1
	s_cmp_ge_u32 s0, 0x7a00
	s_cselect_b32 s33, 1, 0
	s_mul_i32 s1, s33, 0x7a00
	s_sub_i32 s20, s0, s1
	s_cmp_lt_u32 s20, 0x1000
	s_cbranch_scc1 .Lcv4_win
	s_cmp_lt_u32 s20, 0x1800
	s_cbranch_scc1 .Lcv4_wout
	s_cmp_lt_u32 s20, 0x1a00
	s_cbranch_scc1 .Lcv4_glu
	s_cmp_lt_u32 s20, 0x3a00
	s_cbranch_scc1 .Lcv4_w1
	s_cmp_lt_u32 s20, 0x5a00
	s_cbranch_scc1 .Lcv4_w2
	s_cmp_lt_u32 s20, 0x7200
	s_cbranch_scc1 .Lcv4_qkv

; __device__ __forceinline__ unsigned cvt_pk_bf16(float lo, float hi) { unsigned r; asm volatile("v_cvt_pk_bf16_f32 %0, %1, %2" : "=v"(r) : "v"(lo), "v"(hi)); return r; }
; __device__ __forceinline__ void conv_tile(const float* src, bf16_t* dst, int K, int N, int tile, int lane, const float* gk) {
;     const int tn = N >> 5; const int k0 = (tile / tn) * 64, n0 = (tile % tn) * 32; const int kg = lane & 7, jn = lane >> 3;
;     f32x4 v[8]; const float* sp = src + (size_t)(k0 + 8 * kg) * N + n0 + 4 * jn;
; #pragma unroll
;     for (int r = 0; r < 8; ++r) v[r] = *(const f32x4*)(sp + (size_t)r * N);
;     if (gk) { const f32x4 g0 = *(const f32x4*)(gk + k0 + 8 * kg), g1 = *(const f32x4*)(gk + k0 + 8 * kg + 4);
; #pragma unroll
;         for (int r = 0; r < 4; ++r) { v[r] *= g0[r]; v[4 + r] *= g1[r]; } }
; #pragma unroll
;     for (int i = 0; i < 4; ++i) { u32x4 w; w.x = cvt_pk_bf16(v[0][i], v[1][i]); w.y = cvt_pk_bf16(v[2][i], v[3][i]); w.z = cvt_pk_bf16(v[4][i], v[5][i]); w.w = cvt_pk_bf16(v[6][i], v[7][i]);
;         *(u32x4*)(dst + (size_t)(n0 + 4 * jn + i) * K + k0 + 8 * kg) = w; }
.Lcv4_dd:
	s_lshl_b32 s1, s10, 6
	s_mul_i32 s1, s1, s22
	s_lshl_b32 s24, s23, 7
	s_add_u32 s1, s1, s24
	s_add_u32 s4, s4, s1
	s_addc_u32 s5, s5, 0
	s_lshl_b32 s1, s11, 5
	s_mul_i32 s1, s1, s23
	s_lshl_b32 s24, s22, 7
	s_add_u32 s1, s1, s24
	s_add_u32 s72, s6, s1
	s_addc_u32 s73, s7, 0
	s_mov_b32 s74, s11
	s_lshl_b32 s1, s22, 8
	s_cmp_eq_u32 s75, 0
	s_cselect_b32 s8, s4, s8
	s_cselect_b32 s9, s5, s9
	s_cselect_b32 s1, 0, s1
	s_add_u32 s8, s8, s1
	s_addc_u32 s9, s9, 0
	s_lshl_b32 s1, s10, 3
	v_mul_lo_u32 v6, v2, s1
	v_add_u32_e32 v6, v6, v5
	s_lshl_b32 s1, s11, 2
	v_mul_lo_u32 v48, v3, s1
	v_add_u32_e32 v48, v48, v4
	global_load_dwordx4 v[8:11], v6, s[4:5]
	v_add_u32_e32 v6, s10, v6
	global_load_dwordx4 v[12:15], v6, s[4:5]
	v_add_u32_e32 v6, s10, v6
	global_load_dwordx4 v[16:19], v6, s[4:5]
	v_add_u32_e32 v6, s10, v6
	global_load_dwordx4 v[20:23], v6, s[4:5]
	v_add_u32_e32 v6, s10, v6
	global_load_dwordx4 v[24:27], v6, s[4:5]
	v_add_u32_e32 v6, s10, v6
	global_load_dwordx4 v[28:31], v6, s[4:5]
	v_add_u32_e32 v6, s10, v6
	global_load_dwordx4 v[32:35], v6, s[4:5]
	v_add_u32_e32 v6, s10, v6
	global_load_dwordx4 v[36:39], v6, s[4:5]
	global_load_dwordx4 v[40:43], v7, s[8:9]
	global_load_dwordx4 v[44:47], v7, s[8:9] offset:16
	s_waitcnt vmcnt(24)
	s_cmp_eq_u32 s79, 0
	s_cbranch_scc1 .Lcv5_nog
	v_mul_f32_e32 v52, v84, v52
	v_mul_f32_e32 v53, v84, v53
	v_mul_f32_e32 v54, v84, v54
	v_mul_f32_e32 v55, v84, v55
	v_mul_f32_e32 v56, v85, v56
	v_mul_f32_e32 v57, v85, v57
	v_mul_f32_e32 v58, v85, v58
	v_mul_f32_e32 v59, v85, v59
	v_mul_f32_e32 v60, v86, v60
	v_mul_f32_e32 v61, v86, v61
	v_mul_f32_e32 v62, v86, v62
	v_mul_f32_e32 v63, v86, v63
	v_mul_f32_e32 v64, v87, v64
	v_mul_f32_e32 v65, v87, v65
	v_mul_f32_e32 v66, v87, v66
	v_mul_f32_e32 v67, v87, v67
	v_mul_f32_e32 v68, v88, v68
	v_mul_f32_e32 v69, v88, v69
	v_mul_f32_e32 v70, v88, v70
	v_mul_f32_e32 v71, v88, v71
	v_mul_f32_e32 v72, v89, v72
	v_mul_f32_e32 v73, v89, v73
	v_mul_f32_e32 v74, v89, v74
	v_mul_f32_e32 v75, v89, v75
	v_mul_f32_e32 v76, v90, v76
	v_mul_f32_e32 v77, v90, v77
	v_mul_f32_e32 v78, v90, v78
	v_mul_f32_e32 v79, v90, v79
	v_mul_f32_e32 v80, v91, v80
	v_mul_f32_e32 v81, v91, v81
	v_mul_f32_e32 v82, v91, v82
	v_mul_f32_e32 v83, v91, v83
.Lcv5_nog:
	v_cvt_pk_bf16_f32 v84, v52, v56
	v_cvt_pk_bf16_f32 v85, v60, v64
	v_cvt_pk_bf16_f32 v86, v68, v72
	v_cvt_pk_bf16_f32 v87, v76, v80
	global_store_dwordx4 v92, v[84:87], s[76:77]
	v_add_u32_e32 v92, s78, v92
	v_cvt_pk_bf16_f32 v88, v53, v57
	v_cvt_pk_bf16_f32 v89, v61, v65
	v_cvt_pk_bf16_f32 v90, v69, v73
	v_cvt_pk_bf16_f32 v91, v77, v81
	global_store_dwordx4 v92, v[88:91], s[76:77]
	v_add_u32_e32 v92, s78, v92
	v_cvt_pk_bf16_f32 v84, v54, v58
	v_cvt_pk_bf16_f32 v85, v62, v66
	v_cvt_pk_bf16_f32 v86, v70, v74
	v_cvt_pk_bf16_f32 v87, v78, v82
	global_store_dwordx4 v92, v[84:87], s[76:77]
	v_add_u32_e32 v92, s78, v92
	v_cvt_pk_bf16_f32 v88, v55, v59
	v_cvt_pk_bf16_f32 v89, v63, v67
	v_cvt_pk_bf16_f32 v90, v71, v75
	v_cvt_pk_bf16_f32 v91, v79, v83
	global_store_dwordx4 v92, v[88:91], s[76:77]
	s_min_u32 s0, s30, s25
	s_lshl_b32 s0, s0, 10
	s_add_i32 s0, s0, s3
	s_add_i32 s30, s30, 1
	s_cmp_ge_u32 s0, 0x7a00
	s_cselect_b32 s33, 1, 0
	s_mul_i32 s1, s33, 0x7a00
	s_sub_i32 s20, s0, s1
	s_cmp_lt_u32 s20, 0x1000
	s_cbranch_scc1 .Lcv6_win
	s_cmp_lt_u32 s20, 0x1800
	s_cbranch_scc1 .Lcv6_wout
	s_cmp_lt_u32 s20, 0x1a00
	s_cbranch_scc1 .Lcv6_glu
	s_cmp_lt_u32 s20, 0x3a00
	s_cbranch_scc1 .Lcv6_w1
	s_cmp_lt_u32 s20, 0x5a00
	s_cbranch_scc1 .Lcv6_w2
	s_cmp_lt_u32 s20, 0x7200
	s_cbranch_scc1 .Lcv6_qkv

; __device__ __forceinline__ unsigned cvt_pk_bf16(float lo, float hi) { unsigned r; asm volatile("v_cvt_pk_bf16_f32 %0, %1, %2" : "=v"(r) : "v"(lo), "v"(hi)); return r; }
; __device__ __forceinline__ void conv_tile(const float* src, bf16_t* dst, int K, int N, int tile, int lane, const float* gk) {
;     const int tn = N >> 5; const int k0 = (tile / tn) * 64, n0 = (tile % tn) * 32; const int kg = lane & 7, jn = lane >> 3;
;     f32x4 v[8]; const float* sp = src + (size_t)(k0 + 8 * kg) * N + n0 + 4 * jn;
; #pragma unroll
;     for (int r = 0; r < 8; ++r) v[r] = *(const f32x4*)(sp + (size_t)r * N);
;     if (gk) { const f32x4 g0 = *(const f32x4*)(gk + k0 + 8 * kg), g1 = *(const f32x4*)(gk + k0 + 8 * kg + 4);
; #pragma unroll
;         for (int r = 0; r < 4; ++r) { v[r] *= g0[r]; v[4 + r] *= g1[r]; } }
; #pragma unroll
;     for (int i = 0; i < 4; ++i) { u32x4 w; w.x = cvt_pk_bf16(v[0][i], v[1][i]); w.y = cvt_pk_bf16(v[2][i], v[3][i]); w.z = cvt_pk_bf16(v[4][i], v[5][i]); w.w = cvt_pk_bf16(v[6][i], v[7][i]);
;         *(u32x4*)(dst + (size_t)(n0 + 4 * jn + i) * K + k0 + 8 * kg) = w; }
.Lcv6_dd:
	s_lshl_b32 s1, s10, 6
	s_mul_i32 s1, s1, s22
	s_lshl_b32 s24, s23, 7
	s_add_u32 s1, s1, s24
	s_add_u32 s4, s4, s1
	s_addc_u32 s5, s5, 0
	s_lshl_b32 s1, s11, 5
	s_mul_i32 s1, s1, s23
	s_lshl_b32 s24, s22, 7
	s_add_u32 s1, s1, s24
	s_add_u32 s76, s6, s1
	s_addc_u32 s77, s7, 0
	s_mov_b32 s78, s11
	s_lshl_b32 s1, s22, 8
	s_cmp_eq_u32 s79, 0
	s_cselect_b32 s8, s4, s8
	s_cselect_b32 s9, s5, s9
	s_cselect_b32 s1, 0, s1
	s_add_u32 s8, s8, s1
	s_addc_u32 s9, s9, 0
	s_lshl_b32 s1, s10, 3
	v_mul_lo_u32 v6, v2, s1
	v_add_u32_e32 v6, v6, v5
	s_lshl_b32 s1, s11, 2
	v_mul_lo_u32 v92, v3, s1
	v_add_u32_e32 v92, v92, v4
	global_load_dwordx4 v[52:55], v6, s[4:5]
	v_add_u32_e32 v6, s10, v6
	global_load_dwordx4 v[56:59], v6, s[4:5]
	v_add_u32_e32 v6, s10, v6
	global_load_dwordx4 v[60:63], v6, s[4:5]
	v_add_u32_e32 v6, s10, v6
	global_load_dwordx4 v[64:67], v6, s[4:5]
	v_add_u32_e32 v6, s10, v6
	global_load_dwordx4 v[68:71], v6, s[4:5]
	v_add_u32_e32 v6, s10, v6
	global_load_dwordx4 v[72:75], v6, s[4:5]
	v_add_u32_e32 v6, s10, v6
	global_load_dwordx4 v[76:79], v6, s[4:5]
	v_add_u32_e32 v6, s10, v6
	global_load_dwordx4 v[80:83], v6, s[4:5]
	global_load_dwordx4 v[84:87], v7, s[8:9]
	global_load_dwordx4 v[88:91], v7, s[8:9] offset:16
	s_mov_b32 s38, 0
.Lcv_loop:
	s_waitcnt vmcnt(28)
	s_cmp_eq_u32 s83, 0
	s_cbranch_scc1 .Lcv7_nog
	v_mul_f32_e32 v96, v128, v96
	v_mul_f32_e32 v97, v128, v97
	v_mul_f32_e32 v98, v128, v98
	v_mul_f32_e32 v99, v128, v99
	v_mul_f32_e32 v100, v129, v100
	v_mul_f32_e32 v101, v129, v101
	v_mul_f32_e32 v102, v129, v102
	v_mul_f32_e32 v103, v129, v103
	v_mul_f32_e32 v104, v130, v104
	v_mul_f32_e32 v105, v130, v105
	v_mul_f32_e32 v106, v130, v106
	v_mul_f32_e32 v107, v130, v107
	v_mul_f32_e32 v108, v131, v108
	v_mul_f32_e32 v109, v131, v109
	v_mul_f32_e32 v110, v131, v110
	v_mul_f32_e32 v111, v131, v111
	v_mul_f32_e32 v112, v132, v112
	v_mul_f32_e32 v113, v132, v113
	v_mul_f32_e32 v114, v132, v114
	v_mul_f32_e32 v115, v132, v115
	v_mul_f32_e32 v116, v133, v116
	v_mul_f32_e32 v117, v133, v117
	v_mul_f32_e32 v118, v133, v118
	v_mul_f32_e32 v119, v133, v119
	v_mul_f32_e32 v120, v134, v120
	v_mul_f32_e32 v121, v134, v121
	v_mul_f32_e32 v122, v134, v122
	v_mul_f32_e32 v123, v134, v123
	v_mul_f32_e32 v124, v135, v124
	v_mul_f32_e32 v125, v135, v125
	v_mul_f32_e32 v126, v135, v126
	v_mul_f32_e32 v127, v135, v127
.Lcv7_nog:
	v_cvt_pk_bf16_f32 v128, v96, v100
	v_cvt_pk_bf16_f32 v129, v104, v108
	v_cvt_pk_bf16_f32 v130, v112, v116
	v_cvt_pk_bf16_f32 v131, v120, v124
	global_store_dwordx4 v136, v[128:131], s[80:81]
	v_add_u32_e32 v136, s82, v136
	v_cvt_pk_bf16_f32 v132, v97, v101
	v_cvt_pk_bf16_f32 v133, v105, v109
	v_cvt_pk_bf16_f32 v134, v113, v117
	v_cvt_pk_bf16_f32 v135, v121, v125
	global_store_dwordx4 v136, v[132:135], s[80:81]
	v_add_u32_e32 v136, s82, v136
	v_cvt_pk_bf16_f32 v128, v98, v102
	v_cvt_pk_bf16_f32 v129, v106, v110
	v_cvt_pk_bf16_f32 v130, v114, v118
	v_cvt_pk_bf16_f32 v131, v122, v126
	global_store_dwordx4 v136, v[128:131], s[80:81]
	v_add_u32_e32 v136, s82, v136
	v_cvt_pk_bf16_f32 v132, v99, v103
	v_cvt_pk_bf16_f32 v133, v107, v111
	v_cvt_pk_bf16_f32 v134, v115, v119
	v_cvt_pk_bf16_f32 v135, v123, v127
	global_store_dwordx4 v136, v[132:135], s[80:81]
	s_min_u32 s0, s30, s25
	s_lshl_b32 s0, s0, 10
	s_add_i32 s0, s0, s3
	s_add_i32 s30, s30, 1
	s_cmp_ge_u32 s0, 0x7a00
	s_cselect_b32 s33, 1, 0
	s_mul_i32 s1, s33, 0x7a00
	s_sub_i32 s20, s0, s1
	s_cmp_lt_u32 s20, 0x1000
	s_cbranch_scc1 .Lcv8_win
	s_cmp_lt_u32 s20, 0x1800
	s_cbranch_scc1 .Lcv8_wout
	s_cmp_lt_u32 s20, 0x1a00
	s_cbranch_scc1 .Lcv8_glu
	s_cmp_lt_u32 s20, 0x3a00
	s_cbranch_scc1 .Lcv8_w1
	s_cmp_lt_u32 s20, 0x5a00
	s_cbranch_scc1 .Lcv8_w2
	s_cmp_lt_u32 s20, 0x7200
	s_cbranch_scc1 .Lcv8_qkv

; __device__ __forceinline__ void conv_tile(const float* src, bf16_t* dst, int K, int N, int tile, int lane, const float* gk) {
;     const int tn = N >> 5; const int k0 = (tile / tn) * 64, n0 = (tile % tn) * 32; const int kg = lane & 7, jn = lane >> 3;
;     f32x4 v[8]; const float* sp = src + (size_t)(k0 + 8 * kg) * N + n0 + 4 * jn;
; #pragma unroll
;     for (int r = 0; r < 8; ++r) v[r] = *(const f32x4*)(sp + (size_t)r * N);
;     if (gk) { const f32x4 g0 = *(const f32x4*)(gk + k0 + 8 * kg), g1 = *(const f32x4*)(gk + k0 + 8 * kg + 4);
; #pragma unroll
;         for (int r = 0; r < 4; ++r) { v[r] *= g0[r]; v[4 + r] *= g1[r]; } }
.Lcv8_dd:
	s_lshl_b32 s1, s10, 6
	s_mul_i32 s1, s1, s22
	s_lshl_b32 s24, s23, 7
	s_add_u32 s1, s1, s24
	s_add_u32 s4, s4, s1
	s_addc_u32 s5, s5, 0
	s_lshl_b32 s1, s11, 5
	s_mul_i32 s1, s1, s23
	s_lshl_b32 s24, s22, 7
	s_add_u32 s1, s1, s24
	s_add_u32 s80, s6, s1
	s_addc_u32 s81, s7, 0
	s_mov_b32 s82, s11
	s_lshl_b32 s1, s22, 8
	s_cmp_eq_u32 s83, 0
	s_cselect_b32 s8, s4, s8
	s_cselect_b32 s9, s5, s9
	s_cselect_b32 s1, 0, s1
	s_add_u32 s8, s8, s1
	s_addc_u32 s9, s9, 0
	s_lshl_b32 s1, s10, 3
	v_mul_lo_u32 v6, v2, s1
	v_add_u32_e32 v6, v6, v5
	s_lshl_b32 s1, s11, 2
	v_mul_lo_u32 v136, v3, s1
	v_add_u32_e32 v136, v136, v4
	global_load_dwordx4 v[96:99], v6, s[4:5]
	v_add_u32_e32 v6, s10, v6
	global_load_dwordx4 v[100:103], v6, s[4:5]
	v_add_u32_e32 v6, s10, v6
	global_load_dwordx4 v[104:107], v6, s[4:5]
	v_add_u32_e32 v6, s10, v6
	global_load_dwordx4 v[108:111], v6, s[4:5]
	v_add_u32_e32 v6, s10, v6
	global_load_dwordx4 v[112:115], v6, s[4:5]
	v_add_u32_e32 v6, s10, v6
	global_load_dwordx4 v[116:119], v6, s[4:5]
	v_add_u32_e32 v6, s10, v6
	global_load_dwordx4 v[120:123], v6, s[4:5]
	v_add_u32_e32 v6, s10, v6
	global_load_dwordx4 v[124:127], v6, s[4:5]
	global_load_dwordx4 v[128:131], v7, s[8:9]
	global_load_dwordx4 v[132:135], v7, s[8:9] offset:16
	s_waitcnt vmcnt(28)
	s_cmp_eq_u32 s75, 0
	s_cbranch_scc1 .Lcv9_nog
	v_mul_f32_e32 v8, v40, v8
	v_mul_f32_e32 v9, v40, v9
	v_mul_f32_e32 v10, v40, v10
	v_mul_f32_e32 v11, v40, v11
	v_mul_f32_e32 v12, v41, v12
	v_mul_f32_e32 v13, v41, v13
	v_mul_f32_e32 v14, v41, v14
	v_mul_f32_e32 v15, v41, v15
	v_mul_f32_e32 v16, v42, v16
	v_mul_f32_e32 v17, v42, v17
	v_mul_f32_e32 v18, v42, v18
	v_mul_f32_e32 v19, v42, v19
	v_mul_f32_e32 v20, v43, v20
	v_mul_f32_e32 v21, v43, v21
	v_mul_f32_e32 v22, v43, v22
	v_mul_f32_e32 v23, v43, v23
	v_mul_f32_e32 v24, v44, v24
	v_mul_f32_e32 v25, v44, v25
	v_mul_f32_e32 v26, v44, v26
	v_mul_f32_e32 v27, v44, v27
	v_mul_f32_e32 v28, v45, v28
	v_mul_f32_e32 v29, v45, v29
	v_mul_f32_e32 v30, v45, v30
	v_mul_f32_e32 v31, v45, v31
	v_mul_f32_e32 v32, v46, v32
	v_mul_f32_e32 v33, v46, v33
	v_mul_f32_e32 v34, v46, v34
	v_mul_f32_e32 v35, v46, v35
	v_mul_f32_e32 v36, v47, v36
	v_mul_f32_e32 v37, v47, v37
	v_mul_f32_e32 v38, v47, v38
	v_mul_f32_e32 v39, v47, v39

; __device__ __forceinline__ void conv_tile(const float* src, bf16_t* dst, int K, int N, int tile, int lane, const float* gk) {
;     const int tn = N >> 5; const int k0 = (tile / tn) * 64, n0 = (tile % tn) * 32; const int kg = lane & 7, jn = lane >> 3;
;     f32x4 v[8]; const float* sp = src + (size_t)(k0 + 8 * kg) * N + n0 + 4 * jn;
; #pragma unroll
;     for (int r = 0; r < 8; ++r) v[r] = *(const f32x4*)(sp + (size_t)r * N);
;     if (gk) { const f32x4 g0 = *(const f32x4*)(gk + k0 + 8 * kg), g1 = *(const f32x4*)(gk + k0 + 8 * kg + 4);
; #pragma unroll
;         for (int r = 0; r < 4; ++r) { v[r] *= g0[r]; v[4 + r] *= g1[r]; } }
.Lcv10_dd:
	s_lshl_b32 s1, s10, 6
	s_mul_i32 s1, s1, s22
	s_lshl_b32 s24, s23, 7
	s_add_u32 s1, s1, s24
	s_add_u32 s4, s4, s1
	s_addc_u32 s5, s5, 0
	s_lshl_b32 s1, s11, 5
	s_mul_i32 s1, s1, s23
	s_lshl_b32 s24, s22, 7
	s_add_u32 s1, s1, s24
	s_add_u32 s72, s6, s1
	s_addc_u32 s73, s7, 0
	s_mov_b32 s74, s11
	s_lshl_b32 s1, s22, 8
	s_cmp_eq_u32 s75, 0
	s_cselect_b32 s8, s4, s8
	s_cselect_b32 s9, s5, s9
	s_cselect_b32 s1, 0, s1
	s_add_u32 s8, s8, s1
	s_addc_u32 s9, s9, 0
	s_lshl_b32 s1, s10, 3
	v_mul_lo_u32 v6, v2, s1
	v_add_u32_e32 v6, v6, v5
	s_lshl_b32 s1, s11, 2
	v_mul_lo_u32 v48, v3, s1
	v_add_u32_e32 v48, v48, v4
	global_load_dwordx4 v[8:11], v6, s[4:5]
	v_add_u32_e32 v6, s10, v6
	global_load_dwordx4 v[12:15], v6, s[4:5]
	v_add_u32_e32 v6, s10, v6
	global_load_dwordx4 v[16:19], v6, s[4:5]
	v_add_u32_e32 v6, s10, v6
	global_load_dwordx4 v[20:23], v6, s[4:5]
	v_add_u32_e32 v6, s10, v6
	global_load_dwordx4 v[24:27], v6, s[4:5]
	v_add_u32_e32 v6, s10, v6
	global_load_dwordx4 v[28:31], v6, s[4:5]
	v_add_u32_e32 v6, s10, v6
	global_load_dwordx4 v[32:35], v6, s[4:5]
	v_add_u32_e32 v6, s10, v6
	global_load_dwordx4 v[36:39], v6, s[4:5]
	global_load_dwordx4 v[40:43], v7, s[8:9]
	global_load_dwordx4 v[44:47], v7, s[8:9] offset:16
	s_waitcnt vmcnt(28)
	s_cmp_eq_u32 s79, 0
	s_cbranch_scc1 .Lcv11_nog
	v_mul_f32_e32 v52, v84, v52
	v_mul_f32_e32 v53, v84, v53
	v_mul_f32_e32 v54, v84, v54
	v_mul_f32_e32 v55, v84, v55
	v_mul_f32_e32 v56, v85, v56
	v_mul_f32_e32 v57, v85, v57
	v_mul_f32_e32 v58, v85, v58
	v_mul_f32_e32 v59, v85, v59
	v_mul_f32_e32 v60, v86, v60
	v_mul_f32_e32 v61, v86, v61
	v_mul_f32_e32 v62, v86, v62
	v_mul_f32_e32 v63, v86, v63
	v_mul_f32_e32 v64, v87, v64
	v_mul_f32_e32 v65, v87, v65
	v_mul_f32_e32 v66, v87, v66
	v_mul_f32_e32 v67, v87, v67
	v_mul_f32_e32 v68, v88, v68
	v_mul_f32_e32 v69, v88, v69
	v_mul_f32_e32 v70, v88, v70
	v_mul_f32_e32 v71, v88, v71
	v_mul_f32_e32 v72, v89, v72
	v_mul_f32_e32 v73, v89, v73
	v_mul_f32_e32 v74, v89, v74
	v_mul_f32_e32 v75, v89, v75
	v_mul_f32_e32 v76, v90, v76
	v_mul_f32_e32 v77, v90, v77
	v_mul_f32_e32 v78, v90, v78
	v_mul_f32_e32 v79, v90, v79
	v_mul_f32_e32 v80, v91, v80
	v_mul_f32_e32 v81, v91, v81
	v_mul_f32_e32 v82, v91, v82
	v_mul_f32_e32 v83, v91, v83

; __device__ __forceinline__ unsigned cvt_pk_bf16(float lo, float hi) { unsigned r; asm volatile("v_cvt_pk_bf16_f32 %0, %1, %2" : "=v"(r) : "v"(lo), "v"(hi)); return r; }
; __device__ __forceinline__ void conv_tile(const float* src, bf16_t* dst, int K, int N, int tile, int lane, const float* gk) {
;     const int tn = N >> 5; const int k0 = (tile / tn) * 64, n0 = (tile % tn) * 32; const int kg = lane & 7, jn = lane >> 3;
;     f32x4 v[8]; const float* sp = src + (size_t)(k0 + 8 * kg) * N + n0 + 4 * jn;
; #pragma unroll
;     for (int r = 0; r < 8; ++r) v[r] = *(const f32x4*)(sp + (size_t)r * N);
;     if (gk) { const f32x4 g0 = *(const f32x4*)(gk + k0 + 8 * kg), g1 = *(const f32x4*)(gk + k0 + 8 * kg + 4);
; #pragma unroll
;         for (int r = 0; r < 4; ++r) { v[r] *= g0[r]; v[4 + r] *= g1[r]; } }
; #pragma unroll
;     for (int i = 0; i < 4; ++i) { u32x4 w; w.x = cvt_pk_bf16(v[0][i], v[1][i]); w.y = cvt_pk_bf16(v[2][i], v[3][i]); w.z = cvt_pk_bf16(v[4][i], v[5][i]); w.w = cvt_pk_bf16(v[6][i], v[7][i]);
;         *(u32x4*)(dst + (size_t)(n0 + 4 * jn + i) * K + k0 + 8 * kg) = w; }
.Lcv12_dd:
	s_lshl_b32 s1, s10, 6
	s_mul_i32 s1, s1, s22
	s_lshl_b32 s24, s23, 7
	s_add_u32 s1, s1, s24
	s_add_u32 s4, s4, s1
	s_addc_u32 s5, s5, 0
	s_lshl_b32 s1, s11, 5
	s_mul_i32 s1, s1, s23
	s_lshl_b32 s24, s22, 7
	s_add_u32 s1, s1, s24
	s_add_u32 s76, s6, s1
	s_addc_u32 s77, s7, 0
	s_mov_b32 s78, s11
	s_lshl_b32 s1, s22, 8
	s_cmp_eq_u32 s79, 0
	s_cselect_b32 s8, s4, s8
	s_cselect_b32 s9, s5, s9
	s_cselect_b32 s1, 0, s1
	s_add_u32 s8, s8, s1
	s_addc_u32 s9, s9, 0
	s_lshl_b32 s1, s10, 3
	v_mul_lo_u32 v6, v2, s1
	v_add_u32_e32 v6, v6, v5
	s_lshl_b32 s1, s11, 2
	v_mul_lo_u32 v92, v3, s1
	v_add_u32_e32 v92, v92, v4
	global_load_dwordx4 v[52:55], v6, s[4:5]
	v_add_u32_e32 v6, s10, v6
	global_load_dwordx4 v[56:59], v6, s[4:5]
	v_add_u32_e32 v6, s10, v6
	global_load_dwordx4 v[60:63], v6, s[4:5]
	v_add_u32_e32 v6, s10, v6
	global_load_dwordx4 v[64:67], v6, s[4:5]
	v_add_u32_e32 v6, s10, v6
	global_load_dwordx4 v[68:71], v6, s[4:5]
	v_add_u32_e32 v6, s10, v6
	global_load_dwordx4 v[72:75], v6, s[4:5]
	v_add_u32_e32 v6, s10, v6
	global_load_dwordx4 v[76:79], v6, s[4:5]
	v_add_u32_e32 v6, s10, v6
	global_load_dwordx4 v[80:83], v6, s[4:5]
	global_load_dwordx4 v[84:87], v7, s[8:9]
	global_load_dwordx4 v[88:91], v7, s[8:9] offset:16
	s_add_i32 s38, s38, 1
	s_cmp_lt_u32 s38, s39
	s_cbranch_scc1 .Lcv_loop
	s_waitcnt vmcnt(28)
	s_cmp_eq_u32 s83, 0
	s_cbranch_scc1 .Lcv13_nog
	v_mul_f32_e32 v96, v128, v96
	v_mul_f32_e32 v97, v128, v97
	v_mul_f32_e32 v98, v128, v98
	v_mul_f32_e32 v99, v128, v99
	v_mul_f32_e32 v100, v129, v100
	v_mul_f32_e32 v101, v129, v101
	v_mul_f32_e32 v102, v129, v102
	v_mul_f32_e32 v103, v129, v103
	v_mul_f32_e32 v104, v130, v104
	v_mul_f32_e32 v105, v130, v105
	v_mul_f32_e32 v106, v130, v106
	v_mul_f32_e32 v107, v130, v107
	v_mul_f32_e32 v108, v131, v108
	v_mul_f32_e32 v109, v131, v109
	v_mul_f32_e32 v110, v131, v110
	v_mul_f32_e32 v111, v131, v111
	v_mul_f32_e32 v112, v132, v112
	v_mul_f32_e32 v113, v132, v113
	v_mul_f32_e32 v114, v132, v114
	v_mul_f32_e32 v115, v132, v115
	v_mul_f32_e32 v116, v133, v116
	v_mul_f32_e32 v117, v133, v117
	v_mul_f32_e32 v118, v133, v118
	v_mul_f32_e32 v119, v133, v119
	v_mul_f32_e32 v120, v134, v120
	v_mul_f32_e32 v121, v134, v121
	v_mul_f32_e32 v122, v134, v122
	v_mul_f32_e32 v123, v134, v123
	v_mul_f32_e32 v124, v135, v124
	v_mul_f32_e32 v125, v135, v125
	v_mul_f32_e32 v126, v135, v126
	v_mul_f32_e32 v127, v135, v127
.Lcv13_nog:
	v_cvt_pk_bf16_f32 v128, v96, v100
	v_cvt_pk_bf16_f32 v129, v104, v108
	v_cvt_pk_bf16_f32 v130, v112, v116
	v_cvt_pk_bf16_f32 v131, v120, v124
	global_store_dwordx4 v136, v[128:131], s[80:81]
	v_add_u32_e32 v136, s82, v136
	v_cvt_pk_bf16_f32 v132, v97, v101
	v_cvt_pk_bf16_f32 v133, v105, v109
	v_cvt_pk_bf16_f32 v134, v113, v117
	v_cvt_pk_bf16_f32 v135, v121, v125
	global_store_dwordx4 v136, v[132:135], s[80:81]
	v_add_u32_e32 v136, s82, v136
	v_cvt_pk_bf16_f32 v128, v98, v102
	v_cvt_pk_bf16_f32 v129, v106, v110
	v_cvt_pk_bf16_f32 v130, v114, v118
	v_cvt_pk_bf16_f32 v131, v122, v126
	global_store_dwordx4 v136, v[128:131], s[80:81]
	v_add_u32_e32 v136, s82, v136
	v_cvt_pk_bf16_f32 v132, v99, v103
	v_cvt_pk_bf16_f32 v133, v107, v111
	v_cvt_pk_bf16_f32 v134, v115, v119
	v_cvt_pk_bf16_f32 v135, v123, v127
	global_store_dwordx4 v136, v[132:135], s[80:81]
	s_waitcnt vmcnt(0)
	s_cmp_eq_u32 s75, 0
	s_cbranch_scc1 .Lcv14_nog
	v_mul_f32_e32 v8, v40, v8
	v_mul_f32_e32 v9, v40, v9
	v_mul_f32_e32 v10, v40, v10
	v_mul_f32_e32 v11, v40, v11
	v_mul_f32_e32 v12, v41, v12
	v_mul_f32_e32 v13, v41, v13
	v_mul_f32_e32 v14, v41, v14
	v_mul_f32_e32 v15, v41, v15
	v_mul_f32_e32 v16, v42, v16
	v_mul_f32_e32 v17, v42, v17
	v_mul_f32_e32 v18, v42, v18
	v_mul_f32_e32 v19, v42, v19
	v_mul_f32_e32 v20, v43, v20
	v_mul_f32_e32 v21, v43, v21
	v_mul_f32_e32 v22, v43, v22
	v_mul_f32_e32 v23, v43, v23
	v_mul_f32_e32 v24, v44, v24
	v_mul_f32_e32 v25, v44, v25
	v_mul_f32_e32 v26, v44, v26
	v_mul_f32_e32 v27, v44, v27
	v_mul_f32_e32 v28, v45, v28
	v_mul_f32_e32 v29, v45, v29
	v_mul_f32_e32 v30, v45, v30
	v_mul_f32_e32 v31, v45, v31
	v_mul_f32_e32 v32, v46, v32
	v_mul_f32_e32 v33, v46, v33
	v_mul_f32_e32 v34, v46, v34
	v_mul_f32_e32 v35, v46, v35
	v_mul_f32_e32 v36, v47, v36
	v_mul_f32_e32 v37, v47, v37
	v_mul_f32_e32 v38, v47, v38
	v_mul_f32_e32 v39, v47, v39
.Lcv14_nog:
	v_cvt_pk_bf16_f32 v40, v8, v12
	v_cvt_pk_bf16_f32 v41, v16, v20
	v_cvt_pk_bf16_f32 v42, v24, v28
	v_cvt_pk_bf16_f32 v43, v32, v36
	global_store_dwordx4 v48, v[40:43], s[72:73]
	v_add_u32_e32 v48, s74, v48
	v_cvt_pk_bf16_f32 v44, v9, v13
	v_cvt_pk_bf16_f32 v45, v17, v21
	v_cvt_pk_bf16_f32 v46, v25, v29
	v_cvt_pk_bf16_f32 v47, v33, v37
	global_store_dwordx4 v48, v[44:47], s[72:73]
	v_add_u32_e32 v48, s74, v48
	v_cvt_pk_bf16_f32 v40, v10, v14
	v_cvt_pk_bf16_f32 v41, v18, v22
	v_cvt_pk_bf16_f32 v42, v26, v30
	v_cvt_pk_bf16_f32 v43, v34, v38
	global_store_dwordx4 v48, v[40:43], s[72:73]
	v_add_u32_e32 v48, s74, v48
	v_cvt_pk_bf16_f32 v44, v11, v15
	v_cvt_pk_bf16_f32 v45, v19, v23
	v_cvt_pk_bf16_f32 v46, v27, v31
	v_cvt_pk_bf16_f32 v47, v35, v39
	global_store_dwordx4 v48, v[44:47], s[72:73]
	s_branch .LBB0_164

; __device__ __forceinline__ unsigned cvt_pk_bf16(float lo, float hi) { unsigned r; asm volatile("v_cvt_pk_bf16_f32 %0, %1, %2" : "=v"(r) : "v"(lo), "v"(hi)); return r; }
; __device__ __forceinline__ void s5_gen(LAS unsigned char* lds, const Params& P, int j, int g) {
;     ...
;     for (int ch = tid; ch < 256 * 64; ch += NTHR) {
;         const int row = ch >> 6, kc = (ch & 63) * 8, dir = row >> 7, im = (row >> 6) & 1, pp = row & 63, t = kc >> 4, c0 = kc & 15; const int ex = (dir == 0) ? (31 - t) : t;
;         const f32x2 w = pw[(dir * 33 + ex) * 64 + pp]; float v[8];
; #pragma unroll
;         for (int e = 0; e < 8; ++e) { const f32x2 b = bb[(dir * 64 + pp) * 16 + c0 + e]; v[e] = im ? (w.x * b.y + w.y * b.x) : (w.x * b.x - w.y * b.y); }
;         u32x4 wv; wv.x = cvt_pk_bf16(v[0], v[1]); wv.y = cvt_pk_bf16(v[2], v[3]); wv.z = cvt_pk_bf16(v[4], v[5]); wv.w = cvt_pk_bf16(v[6], v[7]);
;         *(u32x4*)(B1 + (size_t)row * 512 + kc) = wv;
;     }
; __global__ void __launch_bounds__(NTHR) hybrid_encoder_fwd(Params P) {
;     ...
;             for (int bt = NB1 + bid * 8 + wid; bt < NBATCH; bt += G * 8) {
; #pragma unroll 1
;                 for (int q = 0; q < 4; ++q) conv_dispatch(P, PREP_TILE(bt) + q, lane); }
.LBB0_116:
	s_movk_i32 s6, 0x2000
	v_lshrrev_b32_e32 v7, 13, v6
	v_and_b32_e32 v8, 63, v4
	v_and_b32_e32 v9, 8, v5
	v_cmp_gt_u32_e32 vcc, s6, v6
	v_and_b32_e32 v12, 0x2000, v6
	v_mul_u32_u24_e32 v7, 33, v7
	v_cndmask_b32_e32 v11, v66, v67, vcc
	v_lshlrev_b32_e32 v14, 3, v8
	v_add_u32_e32 v12, 0, v12
	v_lshlrev_b32_e32 v8, 7, v8
	v_lshlrev_b32_e32 v9, 3, v9
	v_add_u32_e32 v13, 0x200, v6
	s_movk_i32 s6, 0x3dff
	v_add_lshl_u32 v7, v11, v7, 9
	v_add3_u32 v11, v12, v8, v9
	v_and_b32_e32 v86, 0x1000, v6
	v_cmp_lt_u32_e32 vcc, s6, v6
	v_mov_b32_e32 v6, v13
	v_add3_u32 v7, 0, v7, v14
	ds_read_b128 v[12:15], v11 offset:33808
	ds_read_b128 v[16:19], v11 offset:33824
	ds_read_b128 v[20:23], v11 offset:33840
	ds_read_b64 v[8:9], v7
	ds_read_b128 v[24:27], v11 offset:33792
	s_or_b64 s[0:1], vcc, s[0:1]
	v_cmp_eq_u32_e32 vcc, 0, v86
	s_mov_b64 s[6:7], 0x2000
	s_waitcnt lgkmcnt(1)
	v_pk_mul_f32 v[32:33], v[8:9], v[12:13] op_sel:[0,1] op_sel_hi:[1,0]
	v_pk_mul_f32 v[12:13], v[8:9], v[12:13]
	v_pk_mul_f32 v[34:35], v[8:9], v[14:15] op_sel:[0,1] op_sel_hi:[1,0]
	v_pk_mul_f32 v[14:15], v[8:9], v[14:15]
	v_pk_mul_f32 v[56:57], v[8:9], v[16:17] op_sel:[0,1] op_sel_hi:[1,0]
	v_pk_mul_f32 v[16:17], v[8:9], v[16:17]
	v_pk_mul_f32 v[58:59], v[8:9], v[18:19] op_sel:[0,1] op_sel_hi:[1,0]
	v_pk_mul_f32 v[18:19], v[8:9], v[18:19]
	s_waitcnt lgkmcnt(0)
	v_pk_mul_f32 v[28:29], v[8:9], v[24:25] op_sel:[0,1] op_sel_hi:[1,0]
	v_pk_mul_f32 v[24:25], v[8:9], v[24:25]
	v_pk_mul_f32 v[30:31], v[8:9], v[26:27] op_sel:[0,1] op_sel_hi:[1,0]
	v_pk_mul_f32 v[26:27], v[8:9], v[26:27]
	v_pk_mul_f32 v[60:61], v[8:9], v[20:21] op_sel:[0,1] op_sel_hi:[1,0]
	v_pk_mul_f32 v[20:21], v[8:9], v[20:21]
	v_pk_mul_f32 v[84:85], v[8:9], v[22:23] op_sel:[0,1] op_sel_hi:[1,0]
	v_pk_mul_f32 v[8:9], v[8:9], v[22:23]
	v_sub_f32_e32 v12, v12, v13
	v_add_f32_e32 v13, v34, v35
	v_sub_f32_e32 v14, v14, v15
	v_add_f32_e32 v15, v56, v57
	v_sub_f32_e32 v16, v16, v17
	v_add_f32_e32 v17, v58, v59
	v_sub_f32_e32 v18, v18, v19
	v_add_f32_e32 v7, v28, v29
	v_sub_f32_e32 v11, v24, v25
	v_add_f32_e32 v22, v30, v31
	v_sub_f32_e32 v23, v26, v27
	v_add_f32_e32 v24, v32, v33
	v_add_f32_e32 v19, v60, v61
	v_sub_f32_e32 v20, v20, v21
	v_add_f32_e32 v21, v84, v85
	v_sub_f32_e32 v8, v8, v9
	v_cndmask_b32_e32 v13, v13, v14, vcc
	v_cndmask_b32_e32 v14, v15, v16, vcc
	v_cndmask_b32_e32 v15, v17, v18, vcc
	v_add_u32_e32 v5, 0x1000, v5
	v_add_u32_e32 v4, 8, v4
	v_cndmask_b32_e32 v7, v7, v11, vcc
	v_cndmask_b32_e32 v9, v22, v23, vcc
	v_cndmask_b32_e32 v11, v24, v12, vcc
	v_cndmask_b32_e32 v16, v19, v20, vcc
	v_cndmask_b32_e32 v8, v21, v8, vcc
	v_cvt_pk_bf16_f32 v12, v7, v9
	v_cvt_pk_bf16_f32 v13, v11, v13
	v_cvt_pk_bf16_f32 v14, v14, v15
	v_cvt_pk_bf16_f32 v15, v16, v8
	global_store_dwordx4 v[2:3], v[12:15], off
	v_lshl_add_u64 v[2:3], v[2:3], 0, s[6:7]
	s_andn2_b64 exec, exec, s[0:1]
	s_cbranch_execnz .LBB0_116
	s_or_b64 exec, exec, s[0:1]
	s_add_i32 s29, s29, s94
	s_add_i32 s28, s28, s94
	s_cmpk_gt_i32 s29, 0x7f
	s_barrier
	s_cbranch_scc0 .LBB0_57
	v_readlane_b32 s22, v253, 16
	v_readlane_b32 s23, v253, 17
	s_add_i32 s3, s22, 0xd000
	s_mov_b32 s25, 8
	s_mov_b32 s39, 2
	s_branch .Lcv_entry
